# lever 7.11: attention steady loop back-edge bookkeeping (pointer advance, ring rotation, counter, exit test) computed before the loop-back barriers; only exit branch + one s_mov remain after
# baseline (speedup 1.0000x reference)
.LBB0_382:
	s_waitcnt lgkmcnt(14)
	v_mfma_f32_32x32x16_bf16 v[18:33], v[138:141], v[178:181], v[18:33]
	v_exp_f32_e32 v98, v98
	v_exp_f32_e32 v99, v99
	v_exp_f32_e32 v100, v100
	v_exp_f32_e32 v101, v101
	s_waitcnt lgkmcnt(12)
	v_mfma_f32_32x32x16_bf16 v[2:17], v[138:141], v[174:177], v[2:17]
	v_exp_f32_e32 v102, v102
	v_exp_f32_e32 v103, v103
	v_exp_f32_e32 v104, v104
	v_exp_f32_e32 v105, v105
	v_add_u32_e32 v78, s36, v208
	ds_read_b128 v[62:65], v78
	ds_read_b128 v[174:177], v78 offset:512
	s_waitcnt lgkmcnt(12)
	v_mfma_f32_32x32x16_bf16 v[18:33], v[130:133], v[66:69], v[18:33]
	v_exp_f32_e32 v106, v106
	v_exp_f32_e32 v107, v107
	v_exp_f32_e32 v108, v108
	v_exp_f32_e32 v109, v109
	ds_read_b128 v[178:181], v78 offset:2048
	ds_read_b128 v[170:173], v78 offset:2560
	s_waitcnt lgkmcnt(12)
	v_mfma_f32_32x32x16_bf16 v[2:17], v[130:133], v[70:73], v[2:17]
	v_exp_f32_e32 v110, v110
	v_exp_f32_e32 v111, v111
	v_exp_f32_e32 v112, v112
	v_exp_f32_e32 v113, v113
	ds_read_b128 v[166:169], v78 offset:4096
	ds_read_b128 v[162:165], v78 offset:4608
	s_waitcnt lgkmcnt(12)
	v_mfma_f32_32x32x16_bf16 v[18:33], v[122:125], v[74:77], v[18:33]
	v_exp_f32_e32 v82, v82
	v_exp_f32_e32 v83, v83
	v_exp_f32_e32 v84, v84
	v_exp_f32_e32 v85, v85
	ds_read_b128 v[158:161], v78 offset:6144
	ds_read_b128 v[154:157], v78 offset:6656
	s_waitcnt lgkmcnt(12)
	v_mfma_f32_32x32x16_bf16 v[2:17], v[122:125], v[50:53], v[2:17]
	v_exp_f32_e32 v86, v86
	v_exp_f32_e32 v87, v87
	v_exp_f32_e32 v88, v88
	v_exp_f32_e32 v89, v89
	s_waitcnt lgkmcnt(10)
	v_mfma_f32_32x32x16_bf16 v[18:33], v[114:117], v[54:57], v[18:33]
	v_exp_f32_e32 v90, v90
	v_exp_f32_e32 v91, v91
	v_exp_f32_e32 v92, v92
	v_exp_f32_e32 v93, v93
	s_waitcnt lgkmcnt(8)
	v_mfma_f32_32x32x16_bf16 v[2:17], v[114:117], v[58:61], v[2:17]
	v_exp_f32_e32 v94, v94
	v_exp_f32_e32 v95, v95
	v_exp_f32_e32 v96, v96
	v_exp_f32_e32 v97, v97
	s_add_i32 s22, s36, 0x2000
	s_cmpk_lg_i32 s36, 0x4000
	s_cselect_b32 s35, s22, 0
	s_waitcnt vmcnt(2) lgkmcnt(0)
	s_barrier
	s_andn2_b64 vcc, exec, s[20:21]
	s_cbranch_vccnz .LBB0_384
	s_waitcnt lgkmcnt(0)
	ds_read_b128 v[50:53], v193 offset:49248
	ds_read_b128 v[54:57], v193 offset:49216
	ds_read_b128 v[58:61], v193 offset:49184
	ds_read_b128 v[66:69], v193 offset:49152
	s_waitcnt lgkmcnt(3)
	v_pk_mul_f32 v[30:31], v[30:31], v[50:51]
	s_waitcnt lgkmcnt(2)
	v_pk_mul_f32 v[26:27], v[26:27], v[54:55]
	s_waitcnt lgkmcnt(1)
	v_pk_mul_f32 v[22:23], v[22:23], v[58:59]
	v_pk_mul_f32 v[32:33], v[32:33], v[52:53]
	v_pk_mul_f32 v[28:29], v[28:29], v[56:57]
	v_pk_mul_f32 v[24:25], v[24:25], v[60:61]
	s_waitcnt lgkmcnt(0)
	v_pk_mul_f32 v[20:21], v[20:21], v[68:69]
	v_pk_mul_f32 v[18:19], v[18:19], v[66:67]
	v_pk_mul_f32 v[14:15], v[14:15], v[50:51]
	v_pk_mul_f32 v[10:11], v[10:11], v[54:55]
	v_pk_mul_f32 v[6:7], v[6:7], v[58:59]
	v_pk_mul_f32 v[16:17], v[16:17], v[52:53]
	v_pk_mul_f32 v[12:13], v[12:13], v[56:57]
	v_pk_mul_f32 v[8:9], v[8:9], v[60:61]
	v_pk_mul_f32 v[4:5], v[4:5], v[68:69]
	v_pk_mul_f32 v[2:3], v[2:3], v[66:67]
.LBB0_384:
	v_add_u32_e32 v194, s72, v209
	ds_read_b64_tr_b16 v[150:151], v194 offset:24576
	ds_read_b64_tr_b16 v[152:153], v194 offset:25088
	s_waitcnt lgkmcnt(9)
	v_mfma_f32_32x32x16_bf16 v[66:81], v[62:65], v[142:145], v[34:49]
	v_add_f32_e32 v50, v98, v99
	v_add_f32_e32 v50, v100, v50
	v_add_f32_e32 v50, v101, v50
	v_add_f32_e32 v50, v102, v50
	v_add_f32_e32 v50, v103, v50
	v_cvt_pk_bf16_f32 v138, v98, v99
	v_cvt_pk_bf16_f32 v139, v100, v101
	ds_read_b64_tr_b16 v[146:147], v194 offset:28672
	ds_read_b64_tr_b16 v[148:149], v194 offset:29184
	v_add_f32_e32 v50, v104, v50
	v_add_f32_e32 v50, v105, v50
	v_add_f32_e32 v50, v106, v50
	v_add_f32_e32 v114, v107, v50
	s_waitcnt lgkmcnt(10)
	v_mfma_f32_32x32x16_bf16 v[50:65], v[174:177], v[142:145], v[34:49]
	v_cvt_pk_bf16_f32 v140, v102, v103
	v_cvt_pk_bf16_f32 v141, v104, v105
	ds_read_b64_tr_b16 v[98:99], v194 offset:25600
	ds_read_b64_tr_b16 v[100:101], v194 offset:26112
	s_waitcnt lgkmcnt(11)
	v_mfma_f32_32x32x16_bf16 v[66:81], v[178:181], v[134:137], v[66:81]
	v_add_f32_e32 v102, v108, v114
	v_add_f32_e32 v102, v109, v102
	v_add_f32_e32 v102, v110, v102
	v_add_f32_e32 v114, v111, v102
	v_cvt_pk_bf16_f32 v130, v106, v107
	v_cvt_pk_bf16_f32 v131, v108, v109
	ds_read_b64_tr_b16 v[102:103], v194 offset:29696
	ds_read_b64_tr_b16 v[104:105], v194 offset:30208
	s_waitcnt lgkmcnt(12)
	v_mfma_f32_32x32x16_bf16 v[50:65], v[170:173], v[134:137], v[50:65]
	v_add_f32_e32 v106, v112, v114
	v_add_f32_e32 v106, v113, v106
	v_add_f32_e32 v106, v82, v106
	v_add_f32_e32 v114, v83, v106
	v_cvt_pk_bf16_f32 v132, v110, v111
	v_cvt_pk_bf16_f32 v133, v112, v113
	ds_read_b64_tr_b16 v[106:107], v194 offset:26624
	ds_read_b64_tr_b16 v[108:109], v194 offset:27136
	s_waitcnt lgkmcnt(13)
	v_mfma_f32_32x32x16_bf16 v[66:81], v[166:169], v[126:129], v[66:81]
	v_add_f32_e32 v110, v84, v114
	v_add_f32_e32 v110, v85, v110
	v_add_f32_e32 v110, v86, v110
	v_add_f32_e32 v110, v87, v110
	v_cvt_pk_bf16_f32 v122, v82, v83
	v_cvt_pk_bf16_f32 v123, v84, v85
	ds_read_b64_tr_b16 v[82:83], v194 offset:30720
	ds_read_b64_tr_b16 v[84:85], v194 offset:31232
	s_waitcnt lgkmcnt(14)
	v_mfma_f32_32x32x16_bf16 v[50:65], v[162:165], v[126:129], v[50:65]
	v_add_f32_e32 v110, v88, v110
	v_add_f32_e32 v110, v89, v110
	v_add_f32_e32 v110, v90, v110
	v_add_f32_e32 v110, v91, v110
	v_cvt_pk_bf16_f32 v124, v86, v87
	v_cvt_pk_bf16_f32 v125, v88, v89
	ds_read_b64_tr_b16 v[86:87], v194 offset:27648
	ds_read_b64_tr_b16 v[88:89], v194 offset:28160
	s_waitcnt lgkmcnt(14)
	v_mfma_f32_32x32x16_bf16 v[66:81], v[158:161], v[118:121], v[66:81]
	v_add_f32_e32 v110, v92, v110
	v_add_f32_e32 v110, v93, v110
	v_add_f32_e32 v110, v94, v110
	v_add_f32_e32 v110, v95, v110
	v_cvt_pk_bf16_f32 v114, v90, v91
	v_cvt_pk_bf16_f32 v115, v92, v93
	ds_read_b64_tr_b16 v[90:91], v194 offset:31744
	ds_read_b64_tr_b16 v[92:93], v194 offset:32256
	v_mfma_f32_32x32x16_bf16 v[50:65], v[154:157], v[118:121], v[50:65]
	v_add_f32_e32 v110, v96, v110
	v_add_f32_e32 v110, v97, v110
	v_cvt_pk_bf16_f32 v116, v94, v95
	v_cvt_pk_bf16_f32 v117, v96, v97
	s_add_i32 s20, s36, s29
	s_mov_b32 s21, m0
	s_mov_b32 m0, s20
	s_nop 0
	global_load_lds_dwordx4 v227, s[98:99]
	s_mov_b32 m0, s21
	s_add_i32 s20, s35, s30
	s_mov_b32 s21, m0
	s_mov_b32 m0, s20
	s_nop 0
	global_load_lds_dwordx4 v229, s[100:101]
	s_mov_b32 m0, s21
	v_max_f32_e32 v94, v66, v67
	v_max3_f32 v95, v68, v69, v51
	v_max3_f32 v94, v94, v50, v52
	v_max3_f32 v94, v94, v53, v70
	v_max3_f32 v95, v95, v72, v73
	v_max3_f32 v94, v94, v71, v54
	v_max3_f32 v95, v95, v56, v57
	v_max3_f32 v94, v94, v55, v74
	v_max3_f32 v95, v95, v76, v77
	v_max3_f32 v94, v94, v75, v58
	v_max3_f32 v95, v95, v60, v61
	v_max3_f32 v94, v94, v59, v78
	v_max3_f32 v95, v95, v80, v81
	v_max3_f32 v94, v94, v79, v62
	v_max3_f32 v95, v95, v64, v65
	v_max3_f32 v94, v94, v63, v95
	v_cmp_lt_f32_e32 vcc, s69, v94
	s_cmp_lg_u64 vcc, 0
	v_add_f32_e32 v194, v183, v110
	s_cselect_b64 s[20:21], -1, 0
	s_cbranch_vccnz .LBB0_392
.LBB0_385:
	s_waitcnt lgkmcnt(14)
	v_mfma_f32_32x32x16_bf16 v[18:33], v[138:141], v[150:153], v[18:33]
	v_exp_f32_e32 v66, v66
	v_exp_f32_e32 v67, v67
	v_exp_f32_e32 v68, v68
	v_exp_f32_e32 v69, v69
	s_waitcnt lgkmcnt(12)
	v_mfma_f32_32x32x16_bf16 v[2:17], v[138:141], v[146:149], v[2:17]
	v_exp_f32_e32 v70, v70
	v_exp_f32_e32 v71, v71
	v_exp_f32_e32 v72, v72
	v_exp_f32_e32 v73, v73
	v_add_u32_e32 v94, s35, v208
	ds_read_b128 v[174:177], v94
	ds_read_b128 v[170:173], v94 offset:512
	s_waitcnt lgkmcnt(12)
	v_mfma_f32_32x32x16_bf16 v[18:33], v[130:133], v[98:101], v[18:33]
	v_exp_f32_e32 v74, v74
	v_exp_f32_e32 v75, v75
	v_exp_f32_e32 v76, v76
	v_exp_f32_e32 v77, v77
	ds_read_b128 v[166:169], v94 offset:2048
	ds_read_b128 v[162:165], v94 offset:2560
	s_waitcnt lgkmcnt(12)
	v_mfma_f32_32x32x16_bf16 v[2:17], v[130:133], v[102:105], v[2:17]
	v_exp_f32_e32 v78, v78
	v_exp_f32_e32 v79, v79
	v_exp_f32_e32 v80, v80
	v_exp_f32_e32 v81, v81
	ds_read_b128 v[158:161], v94 offset:4096
	ds_read_b128 v[154:157], v94 offset:4608
	s_waitcnt lgkmcnt(12)
	v_mfma_f32_32x32x16_bf16 v[18:33], v[122:125], v[106:109], v[18:33]
	v_exp_f32_e32 v50, v50
	v_exp_f32_e32 v51, v51
	v_exp_f32_e32 v52, v52
	v_exp_f32_e32 v53, v53
	ds_read_b128 v[150:153], v94 offset:6144
	ds_read_b128 v[146:149], v94 offset:6656
	s_waitcnt lgkmcnt(12)
	v_mfma_f32_32x32x16_bf16 v[2:17], v[122:125], v[82:85], v[2:17]
	v_exp_f32_e32 v54, v54
	v_exp_f32_e32 v55, v55
	v_exp_f32_e32 v56, v56
	v_exp_f32_e32 v57, v57
	s_waitcnt lgkmcnt(10)
	v_mfma_f32_32x32x16_bf16 v[18:33], v[114:117], v[86:89], v[18:33]
	v_exp_f32_e32 v58, v58
	v_exp_f32_e32 v59, v59
	v_exp_f32_e32 v60, v60
	v_exp_f32_e32 v61, v61
	s_waitcnt lgkmcnt(8)
	v_mfma_f32_32x32x16_bf16 v[2:17], v[114:117], v[90:93], v[2:17]
	v_exp_f32_e32 v62, v62
	v_exp_f32_e32 v63, v63
	v_exp_f32_e32 v64, v64
	v_exp_f32_e32 v65, v65
	s_add_u32 s98, s98, s62
	s_addc_u32 s99, s99, s63
	s_add_u32 s100, s100, s62
	s_addc_u32 s101, s101, s63
	s_add_i32 s22, s35, 0x2000
	s_cmpk_lg_i32 s35, 0x4000
	s_cselect_b32 s37, s22, 0
	s_mov_b32 s23, s36
	s_add_i32 s22, s41, 2
	s_cmp_ge_u32 s22, s28
	s_cselect_b32 s41, s41, s22
	s_cselect_b32 s72, s72, s35
	s_cselect_b32 s36, s36, s37
	s_cselect_b32 s22, 1, 0
	s_waitcnt vmcnt(2) lgkmcnt(0)
	s_barrier
	s_andn2_b64 vcc, exec, s[20:21]
	s_cbranch_vccnz .LBB0_387
	s_waitcnt lgkmcnt(0)
	ds_read_b128 v[82:85], v193 offset:49248
	ds_read_b128 v[86:89], v193 offset:49216
	ds_read_b128 v[90:93], v193 offset:49152
	ds_read_b128 v[94:97], v193 offset:49184
	s_waitcnt lgkmcnt(3)
	v_pk_mul_f32 v[32:33], v[32:33], v[84:85]
	v_pk_mul_f32 v[30:31], v[30:31], v[82:83]
	s_waitcnt lgkmcnt(2)
	v_pk_mul_f32 v[28:29], v[28:29], v[88:89]
	v_pk_mul_f32 v[26:27], v[26:27], v[86:87]
	s_waitcnt lgkmcnt(0)
	v_pk_mul_f32 v[24:25], v[24:25], v[96:97]
	v_pk_mul_f32 v[22:23], v[22:23], v[94:95]
	v_pk_mul_f32 v[20:21], v[20:21], v[92:93]
	v_pk_mul_f32 v[18:19], v[18:19], v[90:91]
	v_pk_mul_f32 v[16:17], v[16:17], v[84:85]
	v_pk_mul_f32 v[14:15], v[14:15], v[82:83]
	v_pk_mul_f32 v[12:13], v[12:13], v[88:89]
	v_pk_mul_f32 v[10:11], v[10:11], v[86:87]
	v_pk_mul_f32 v[8:9], v[8:9], v[96:97]
	v_pk_mul_f32 v[6:7], v[6:7], v[94:95]
	v_pk_mul_f32 v[4:5], v[4:5], v[92:93]
	v_pk_mul_f32 v[2:3], v[2:3], v[90:91]
.LBB0_387:
	s_cmp_lg_u32 s22, 0
	s_cbranch_scc1 .LBB0_402
	s_mov_b32 s20, s23
	s_branch .LBB0_381
